# nt stores: Q fragments, f32 k/v state outputs, bf16 p copy
# speedup vs baseline: 1.0187x; 1.0187x over previous
; __device__ __forceinline__ unsigned pk2(float lo, float hi) { return pg8::cvt_pk_bf16_v(lo, hi); }
; __device__ __forceinline__ void phase0(const Params& P, LAS unsigned char* lds, int tid, int lane, int wave, int G) {
;     ...
;     for (int m0 = gw; m0 < M; m0 += 4 * NGW) {
;         f32x4 pv[4];
; #pragma unroll
;         for (int k = 0; k < 4; ++k) { const int m = m0 + k * NGW; if (m < M) { const float* prow = m < MP ? P.p_p + (size_t)m * 256 : P.p_s + (size_t)(m - MP) * 256; pv[k] = ((const f32x4*)prow)[lane]; } }
; #pragma unroll
;         for (int k = 0; k < 4; ++k) { const int m = m0 + k * NGW; if (m < M) { v2u o; o.x = pk2(pv[k][0], pv[k][1]); o.y = pk2(pv[k][2], pv[k][3]); ((v2u*)(PB + (size_t)m * 256))[lane] = o; } }
;     }
.LBB0_72:
	s_lshl_b64 s[6:7], s[6:7], 9
	s_waitcnt vmcnt(0)
	v_cvt_pk_bf16_f32 v14, v14, v15
	v_cvt_pk_bf16_f32 v15, v16, v17
	v_lshl_add_u64 v[16:17], v[18:19], 0, s[6:7]
	s_andn2_b64 vcc, exec, s[26:27]
	global_store_dwordx2 v[16:17], v[14:15], off nt
	s_cbranch_vccnz .LBB0_75
	s_ashr_i32 s9, s8, 31
	s_lshl_b64 s[6:7], s[8:9], 9
	v_cvt_pk_bf16_f32 v14, v10, v11
	v_cvt_pk_bf16_f32 v15, v12, v13
	v_lshl_add_u64 v[16:17], v[18:19], 0, s[6:7]
	global_store_dwordx2 v[16:17], v[14:15], off nt
	s_andn2_b64 vcc, exec, s[30:31]
	s_cbranch_vccz .LBB0_76

; __device__ __forceinline__ unsigned pk2(float lo, float hi) { return pg8::cvt_pk_bf16_v(lo, hi); }
; __device__ __forceinline__ void phase0(const Params& P, LAS unsigned char* lds, int tid, int lane, int wave, int G) {
;     ...
;         for (int k = 0; k < 4; ++k) { const int m = m0 + k * NGW; if (m < M) { const float* prow = m < MP ? P.p_p + (size_t)m * 256 : P.p_s + (size_t)(m - MP) * 256; pv[k] = ((const f32x4*)prow)[lane]; } }
; #pragma unroll
;         for (int k = 0; k < 4; ++k) { const int m = m0 + k * NGW; if (m < M) { v2u o; o.x = pk2(pv[k][0], pv[k][1]); o.y = pk2(pv[k][2], pv[k][3]); ((v2u*)(PB + (size_t)m * 256))[lane] = o; } }
;     }
.LBB0_76:
	s_ashr_i32 s11, s10, 31
	s_lshl_b64 s[6:7], s[10:11], 9
	v_cvt_pk_bf16_f32 v14, v6, v7
	v_cvt_pk_bf16_f32 v15, v8, v9
	v_lshl_add_u64 v[16:17], v[18:19], 0, s[6:7]
	global_store_dwordx2 v[16:17], v[14:15], off nt
	s_andn2_b64 vcc, exec, s[34:35]
	s_cbranch_vccnz .LBB0_65
.LBB0_77:
	s_ashr_i32 s29, s28, 31
	s_lshl_b64 s[6:7], s[28:29], 9
	v_cvt_pk_bf16_f32 v14, v2, v3
	v_cvt_pk_bf16_f32 v15, v4, v5
	v_lshl_add_u64 v[16:17], v[18:19], 0, s[6:7]
	global_store_dwordx2 v[16:17], v[14:15], off nt
	s_branch .LBB0_65

; __device__ __forceinline__ void unpack8(v4u w, float (&f)[8]) { f[0] = bflo(w.x); f[1] = bfhi(w.x); f[2] = bflo(w.y); f[3] = bfhi(w.y); f[4] = bflo(w.z); f[5] = bfhi(w.z); f[6] = bflo(w.w); f[7] = bfhi(w.w); }
; __device__ __forceinline__ v4u packf8(const float (&f)[8]) { v4u w; w.x = pk2(f[0], f[1]); w.y = pk2(f[2], f[3]); w.z = pk2(f[4], f[5]); w.w = pk2(f[6], f[7]); return w; }
; __device__ __forceinline__ void bprep_item(const Params& P, LAS unsigned char* lds, int item, int tid, int lane, int wave) {
;     ...
;             if (mode != 2) {
;                 unpack8(wq_[hi], f); float ss = 0.f;
; #pragma unroll
;                 for (int i = 0; i < 8; ++i) ss += f[i] * f[i];
;                 ss += __shfl_xor(ss, 1); ss += __shfl_xor(ss, 2); ss += __shfl_xor(ss, 4);
;                 float rstd = __builtin_amdgcn_rsqf(ss * (1.0f / 64.0f) + 1e-6f);
; #pragma unroll
;                 for (int i = 0; i < 8; ++i) f[i] = f[i] * (rstd * 0.18033688011f) * qg[i];
;                 *(v4u*)(qdst + (qblk * 8 + h) * 4096 + piece) = xchg8x8(xs, lane, packf8(f));
;                 unpack8(wk_[hi], f); ss = 0.f;
; #pragma unroll
;                 for (int i = 0; i < 8; ++i) ss += f[i] * f[i];
;                 ss += __shfl_xor(ss, 1); ss += __shfl_xor(ss, 2); ss += __shfl_xor(ss, 4);
;                 rstd = __builtin_amdgcn_rsqf(ss * (1.0f / 64.0f) + 1e-6f);
; #pragma unroll
;                 for (int i = 0; i < 8; ++i) f[i] = f[i] * rstd * kg[i];
;             } else { f[0] = ck_[hi][0][0]; f[1] = ck_[hi][0][1]; f[2] = ck_[hi][0][2]; f[3] = ck_[hi][0][3]; f[4] = ck_[hi][1][0]; f[5] = ck_[hi][1][1]; f[6] = ck_[hi][1][2]; f[7] = ck_[hi][1][3]; }
;             *(v4u*)(kdst + (kvblk * 8 + h) * 4096 + piece) = xchg8x8(xs, lane, packf8(f));
.LBB0_521:
	s_and_b64 vcc, exec, s[4:5]
	s_mov_b64 s[56:57], -1
	s_cbranch_vccnz .LBB0_523
	s_waitcnt vmcnt(2)
	v_lshlrev_b32_e32 v194, 16, v98
	v_and_b32_e32 v195, 0xffff0000, v98
	v_and_b32_e32 v35, 64, v192
	v_lshlrev_b32_e32 v186, 16, v99
	v_and_b32_e32 v187, 0xffff0000, v99
	v_pk_mul_f32 v[196:197], v[194:195], v[194:195]
	v_xor_b32_e32 v34, 1, v192
	v_add_u32_e32 v193, 64, v35
	v_pk_mul_f32 v[188:189], v[186:187], v[186:187]
	v_add_f32_e32 v196, v196, v197
	v_cmp_lt_i32_e32 vcc, v34, v193
	v_lshlrev_b32_e32 v38, 16, v100
	v_and_b32_e32 v39, 0xffff0000, v100
	v_add_f32_e32 v188, v188, v196
	v_cndmask_b32_e32 v34, v192, v34, vcc
	v_pk_mul_f32 v[40:41], v[38:39], v[38:39]
	v_add_f32_e32 v188, v189, v188
	v_lshlrev_b32_e32 v208, 2, v34
	v_lshlrev_b32_e32 v34, 16, v101
	v_and_b32_e32 v35, 0xffff0000, v101
	v_add_f32_e32 v40, v40, v188
	v_pk_mul_f32 v[36:37], v[34:35], v[34:35]
	v_add_f32_e32 v40, v41, v40
	v_add_f32_e32 v36, v36, v40
	v_add_f32_e32 v36, v37, v36
	ds_bpermute_b32 v37, v208, v36
	v_xor_b32_e32 v40, 2, v192
	v_cmp_lt_i32_e32 vcc, v40, v193
	s_waitcnt vmcnt(1)
	v_lshlrev_b32_e32 v200, 16, v94
	v_and_b32_e32 v201, 0xffff0000, v94
	v_cndmask_b32_e32 v40, v192, v40, vcc
	v_lshlrev_b32_e32 v209, 2, v40
	s_waitcnt lgkmcnt(0)
	v_add_f32_e32 v36, v36, v37
	ds_bpermute_b32 v37, v209, v36
	v_xor_b32_e32 v40, 4, v192
	v_cmp_lt_i32_e32 vcc, v40, v193
	v_pk_mul_f32 v[202:203], v[200:201], v[200:201]
	v_lshlrev_b32_e32 v204, 16, v95
	v_cndmask_b32_e32 v40, v192, v40, vcc
	v_lshlrev_b32_e32 v193, 2, v40
	s_waitcnt lgkmcnt(0)
	v_add_f32_e32 v36, v36, v37
	ds_bpermute_b32 v37, v193, v36
	v_and_b32_e32 v205, 0xffff0000, v95
	v_pk_mul_f32 v[206:207], v[204:205], v[204:205]
	v_and_b32_e32 v188, 0xffff0000, v96
	v_lshlrev_b32_e32 v189, 16, v96
	s_waitcnt lgkmcnt(0)
	v_add_f32_e32 v36, v36, v37
	v_fmamk_f32 v36, v36, 0x3c800000, v171
	v_rsq_f32_e32 v36, v36
	v_and_b32_e32 v196, 0xffff0000, v97
	v_lshlrev_b32_e32 v197, 16, v97
	v_pk_mul_f32 v[198:199], v[196:197], v[196:197]
	v_mul_f32_e32 v36, 0x3e38aa3b, v36
	v_pk_mul_f32 v[40:41], v[36:37], v[194:195] op_sel_hi:[0,1]
	v_pk_mul_f32 v[186:187], v[36:37], v[186:187] op_sel_hi:[0,1]
	v_add_f32_e32 v37, v202, v203
	v_add_f32_e32 v37, v206, v37
	v_pk_mul_f32 v[194:195], v[188:189], v[188:189]
	v_add_f32_e32 v37, v207, v37
	v_add_f32_e32 v37, v195, v37
	v_add_f32_e32 v37, v194, v37
	v_add_f32_e32 v37, v199, v37
	v_add_f32_e32 v37, v198, v37
	ds_bpermute_b32 v194, v208, v37
	v_pk_mul_f32 v[38:39], v[36:37], v[38:39] op_sel_hi:[0,1]
	v_pk_mul_f32 v[34:35], v[36:37], v[34:35] op_sel_hi:[0,1]
	v_pk_mul_f32 v[38:39], v[42:43], v[38:39]
	v_pk_mul_f32 v[40:41], v[46:47], v[40:41]
	s_waitcnt lgkmcnt(0)
	v_add_f32_e32 v37, v37, v194
	ds_bpermute_b32 v198, v209, v37
	v_cvt_pk_bf16_f32 v36, v38, v39
	v_pk_mul_f32 v[186:187], v[48:49], v[186:187]
	v_pk_mul_f32 v[194:195], v[44:45], v[34:35]
	v_cvt_pk_bf16_f32 v34, v40, v41
	s_waitcnt lgkmcnt(0)
	v_add_f32_e32 v38, v37, v198
	ds_bpermute_b32 v39, v193, v38
	v_cvt_pk_bf16_f32 v35, v186, v187
	v_cvt_pk_bf16_f32 v37, v194, v195
	ds_write_b128 v190, v[34:37]
	ds_read_b128 v[34:37], v191
	s_waitcnt lgkmcnt(2)
	v_add_f32_e32 v38, v38, v39
	v_fmamk_f32 v38, v38, 0x3c800000, v171
	v_rsq_f32_e32 v186, v38
	s_lshl_b32 s18, s8, 12
	s_mov_b32 s19, s9
	v_lshl_add_u64 v[38:39], v[180:181], 0, s[18:19]
	s_waitcnt lgkmcnt(0)
	global_store_dwordx4 v[38:39], v[34:37], off nt
	s_nop 1
	v_pk_mul_f32 v[34:35], v[186:187], v[200:201] op_sel_hi:[0,1]
	s_waitcnt vmcnt(1)
	v_pk_mul_f32 v[38:39], v[54:55], v[34:35]
	v_pk_mul_f32 v[34:35], v[186:187], v[204:205] op_sel_hi:[0,1]
	v_pk_mul_f32 v[40:41], v[56:57], v[34:35]
	v_pk_mul_f32 v[34:35], v[186:187], v[188:189] op_sel_hi:[0,1]
	v_pk_mul_f32 v[36:37], v[186:187], v[196:197] op_sel_hi:[0,1]
	v_pk_mul_f32 v[34:35], v[50:51], v[34:35] op_sel:[0,1] op_sel_hi:[1,0]
	v_pk_mul_f32 v[36:37], v[52:53], v[36:37] op_sel:[0,1] op_sel_hi:[1,0]
	s_cbranch_execz .LBB0_524
	s_branch .LBB0_525

; __device__ __forceinline__ v4u packf8(const float (&f)[8]) { v4u w; w.x = pk2(f[0], f[1]); w.y = pk2(f[2], f[3]); w.z = pk2(f[4], f[5]); w.w = pk2(f[6], f[7]); return w; }
; __device__ __forceinline__ void bprep_item(const Params& P, LAS unsigned char* lds, int item, int tid, int lane, int wave) {
;     ...
;             *(v4u*)(kdst + (kvblk * 8 + h) * 4096 + piece) = xchg8x8(xs, lane, packf8(f));
;             {
;                 float* ko = nullptr;
;                 if (mode == 0) { const int ts = c * 64 + tl; if (ts >= TP - 512) ko = P.out + O_KP + (((size_t)s * 512 + (ts - (TP - 512))) * 8 + h) * 64 + 8 * part; }
;                 else if (mode == 1 && valid) ko = P.out + O_KS + (((size_t)s * 16 + tl) * 8 + h) * 64 + 8 * part;
;                 if (ko) { ((f32x4*)ko)[0] = (f32x4){f[0], f[1], f[2], f[3]}; ((f32x4*)ko)[1] = (f32x4){f[4], f[5], f[6], f[7]}; }
.LBB0_525:
	v_cvt_pk_bf16_f32 v186, v38, v39
	v_cvt_pk_bf16_f32 v187, v40, v41
	v_cvt_pk_bf16_f32 v188, v34, v35
	v_cvt_pk_bf16_f32 v189, v36, v37
	ds_write_b128 v190, v[186:189]
	ds_read_b128 v[186:189], v191
	s_lshl_b64 s[18:19], s[8:9], 12
	v_lshl_add_u64 v[194:195], v[178:179], 0, s[18:19]
	s_waitcnt lgkmcnt(0)
	global_store_dwordx4 v[194:195], v[186:189], off
	s_nop 1
	v_or_b32_e32 v186, s8, v150
	v_mov_b32_e32 v187, v1
	v_lshlrev_b64 v[186:187], 8, v[186:187]
	v_lshl_add_u64 v[188:189], v[182:183], 0, v[186:187]
	v_cmp_ne_u64_e32 vcc, 0, v[188:189]
	s_and_b64 s[18:19], s[6:7], vcc
	s_and_saveexec_b64 s[56:57], s[18:19]
	s_cbranch_execz .LBB0_527
	global_store_dwordx4 v[188:189], v[38:41], off nt
	global_store_dwordx4 v[188:189], v[34:37], off offset:16 nt

; __device__ __forceinline__ void bprep_item(const Params& P, LAS unsigned char* lds, int item, int tid, int lane, int wave) {
;     ...
;         for (int hi = 0; hi < 4; ++hi) { const int h = hb4 + hi;
;             float f[8];
;             if (mode != 2) {
;                 unpack8(wq_[hi], f); float ss = 0.f;
; #pragma unroll
;                 for (int i = 0; i < 8; ++i) ss += f[i] * f[i];
;                 ss += __shfl_xor(ss, 1); ss += __shfl_xor(ss, 2); ss += __shfl_xor(ss, 4);
;                 float rstd = __builtin_amdgcn_rsqf(ss * (1.0f / 64.0f) + 1e-6f);
; #pragma unroll
;                 for (int i = 0; i < 8; ++i) f[i] = f[i] * (rstd * 0.18033688011f) * qg[i];
;                 *(v4u*)(qdst + (qblk * 8 + h) * 4096 + piece) = xchg8x8(xs, lane, packf8(f));
;                 unpack8(wk_[hi], f); ss = 0.f;
; #pragma unroll
;                 for (int i = 0; i < 8; ++i) ss += f[i] * f[i];
;                 ss += __shfl_xor(ss, 1); ss += __shfl_xor(ss, 2); ss += __shfl_xor(ss, 4);
;                 rstd = __builtin_amdgcn_rsqf(ss * (1.0f / 64.0f) + 1e-6f);
; #pragma unroll
;                 for (int i = 0; i < 8; ++i) f[i] = f[i] * rstd * kg[i];
;             } else { f[0] = ck_[hi][0][0]; f[1] = ck_[hi][0][1]; f[2] = ck_[hi][0][2]; f[3] = ck_[hi][0][3]; f[4] = ck_[hi][1][0]; f[5] = ck_[hi][1][1]; f[6] = ck_[hi][1][2]; f[7] = ck_[hi][1][3]; }
;             *(v4u*)(kdst + (kvblk * 8 + h) * 4096 + piece) = xchg8x8(xs, lane, packf8(f));
;             {
;                 float* ko = nullptr;
;                 if (mode == 0) { const int ts = c * 64 + tl; if (ts >= TP - 512) ko = P.out + O_KP + (((size_t)s * 512 + (ts - (TP - 512))) * 8 + h) * 64 + 8 * part; }
;                 else if (mode == 1 && valid) ko = P.out + O_KS + (((size_t)s * 16 + tl) * 8 + h) * 64 + 8 * part;
;                 if (ko) { ((f32x4*)ko)[0] = (f32x4){f[0], f[1], f[2], f[3]}; ((f32x4*)ko)[1] = (f32x4){f[4], f[5], f[6], f[7]}; }
;             }
;             if (mode != 2) unpack8(wv_[hi], f);
;             else { f[0] = cv_[hi][0][0]; f[1] = cv_[hi][0][1]; f[2] = cv_[hi][0][2]; f[3] = cv_[hi][0][3]; f[4] = cv_[hi][1][0]; f[5] = cv_[hi][1][1]; f[6] = cv_[hi][1][2]; f[7] = cv_[hi][1][3]; }
;             {
;                 float* vo = nullptr;
.LBB0_530:
	s_andn2_b64 vcc, exec, s[56:57]
	v_lshl_add_u64 v[186:187], v[184:185], 0, v[186:187]
	v_cmp_ne_u64_e32 vcc, 0, v[186:187]
	s_and_b64 s[18:19], s[6:7], vcc
	s_and_saveexec_b64 s[56:57], s[18:19]
	s_cbranch_execz .LBB0_532
	global_store_dwordx4 v[186:187], v[34:37], off nt
	global_store_dwordx4 v[186:187], v[38:41], off offset:16 nt
.LBB0_532:
	s_or_b64 exec, exec, s[56:57]
	v_cvt_pk_bf16_f32 v34, v34, v35
	v_cvt_pk_bf16_f32 v35, v36, v37
	v_cvt_pk_bf16_f32 v36, v38, v39
	v_lshl_add_u32 v38, s8, 6, v138
	v_cvt_pk_bf16_f32 v37, v40, v41
	v_mad_u64_u32 v[38:39], s[18:19], v38, s58, v[158:159]
	s_and_b64 vcc, exec, s[4:5]
	s_mov_b64 s[56:57], -1
	ds_write_b128 v38, v[34:37]
	s_cbranch_vccnz .LBB0_534
	v_lshlrev_b32_e32 v194, 16, v110
	v_and_b32_e32 v195, 0xffff0000, v110
	v_and_b32_e32 v35, 64, v192
	v_lshlrev_b32_e32 v186, 16, v111
	v_and_b32_e32 v187, 0xffff0000, v111
	v_pk_mul_f32 v[196:197], v[194:195], v[194:195]
	v_xor_b32_e32 v34, 1, v192
	v_add_u32_e32 v193, 64, v35
	v_pk_mul_f32 v[188:189], v[186:187], v[186:187]
	v_add_f32_e32 v196, v196, v197
	v_cmp_lt_i32_e32 vcc, v34, v193
	v_lshlrev_b32_e32 v38, 16, v112
	v_and_b32_e32 v39, 0xffff0000, v112
	v_add_f32_e32 v188, v188, v196
	v_cndmask_b32_e32 v34, v192, v34, vcc
	v_pk_mul_f32 v[40:41], v[38:39], v[38:39]
	v_add_f32_e32 v188, v189, v188
	v_lshlrev_b32_e32 v208, 2, v34
	v_lshlrev_b32_e32 v34, 16, v113
	v_and_b32_e32 v35, 0xffff0000, v113
	v_add_f32_e32 v40, v40, v188
	v_pk_mul_f32 v[36:37], v[34:35], v[34:35]
	v_add_f32_e32 v40, v41, v40
	v_add_f32_e32 v36, v36, v40
	v_add_f32_e32 v36, v37, v36
	ds_bpermute_b32 v37, v208, v36
	v_xor_b32_e32 v40, 2, v192
	v_cmp_lt_i32_e32 vcc, v40, v193
	v_lshlrev_b32_e32 v200, 16, v106
	v_and_b32_e32 v201, 0xffff0000, v106
	v_cndmask_b32_e32 v40, v192, v40, vcc
	v_lshlrev_b32_e32 v209, 2, v40
	s_waitcnt lgkmcnt(0)
	v_add_f32_e32 v36, v36, v37
	ds_bpermute_b32 v37, v209, v36
	v_xor_b32_e32 v40, 4, v192
	v_cmp_lt_i32_e32 vcc, v40, v193
	v_pk_mul_f32 v[202:203], v[200:201], v[200:201]
	v_lshlrev_b32_e32 v204, 16, v107
	v_cndmask_b32_e32 v40, v192, v40, vcc
	v_lshlrev_b32_e32 v193, 2, v40
	s_waitcnt lgkmcnt(0)
	v_add_f32_e32 v36, v36, v37
	ds_bpermute_b32 v37, v193, v36
	v_and_b32_e32 v205, 0xffff0000, v107
	v_pk_mul_f32 v[206:207], v[204:205], v[204:205]
	v_and_b32_e32 v188, 0xffff0000, v108
	v_lshlrev_b32_e32 v189, 16, v108
	s_waitcnt lgkmcnt(0)
	v_add_f32_e32 v36, v36, v37
	v_fmamk_f32 v36, v36, 0x3c800000, v171
	v_rsq_f32_e32 v36, v36
	v_and_b32_e32 v196, 0xffff0000, v109
	v_lshlrev_b32_e32 v197, 16, v109
	v_pk_mul_f32 v[198:199], v[196:197], v[196:197]
	v_mul_f32_e32 v36, 0x3e38aa3b, v36
	v_pk_mul_f32 v[40:41], v[36:37], v[194:195] op_sel_hi:[0,1]
	v_add_f32_e32 v37, v202, v203
	v_add_f32_e32 v37, v206, v37
	v_pk_mul_f32 v[194:195], v[188:189], v[188:189]
	v_add_f32_e32 v37, v207, v37
	v_add_f32_e32 v37, v195, v37
	v_add_f32_e32 v37, v194, v37
	v_add_f32_e32 v37, v199, v37
	v_add_f32_e32 v37, v198, v37
	ds_bpermute_b32 v194, v208, v37
	v_pk_mul_f32 v[186:187], v[36:37], v[186:187] op_sel_hi:[0,1]
	v_pk_mul_f32 v[38:39], v[36:37], v[38:39] op_sel_hi:[0,1]
	v_pk_mul_f32 v[40:41], v[46:47], v[40:41]
	v_pk_mul_f32 v[186:187], v[48:49], v[186:187]
	s_waitcnt lgkmcnt(0)
	v_add_f32_e32 v37, v37, v194
	ds_bpermute_b32 v198, v209, v37
	v_pk_mul_f32 v[34:35], v[36:37], v[34:35] op_sel_hi:[0,1]
	v_pk_mul_f32 v[194:195], v[44:45], v[34:35]
	v_cvt_pk_bf16_f32 v34, v40, v41
	v_pk_mul_f32 v[38:39], v[42:43], v[38:39]
	s_waitcnt lgkmcnt(0)
	v_add_f32_e32 v40, v37, v198
	ds_bpermute_b32 v41, v193, v40
	v_cvt_pk_bf16_f32 v35, v186, v187
	v_cvt_pk_bf16_f32 v36, v38, v39
	v_cvt_pk_bf16_f32 v37, v194, v195
	ds_write_b128 v190, v[34:37]
	s_waitcnt lgkmcnt(1)
	v_add_f32_e32 v38, v40, v41
	ds_read_b128 v[34:37], v191
	v_fmamk_f32 v38, v38, 0x3c800000, v171
	v_rsq_f32_e32 v186, v38
	s_lshl_b32 s8, s52, 12
	v_lshl_add_u64 v[38:39], v[180:181], 0, s[8:9]
	s_waitcnt lgkmcnt(0)
	global_store_dwordx4 v[38:39], v[34:37], off nt
	s_mov_b64 s[56:57], 0
	s_nop 0
	v_pk_mul_f32 v[34:35], v[186:187], v[200:201] op_sel_hi:[0,1]
	v_pk_mul_f32 v[38:39], v[54:55], v[34:35]
	v_pk_mul_f32 v[34:35], v[186:187], v[204:205] op_sel_hi:[0,1]
	v_pk_mul_f32 v[40:41], v[56:57], v[34:35]
	v_pk_mul_f32 v[34:35], v[186:187], v[188:189] op_sel_hi:[0,1]
	v_pk_mul_f32 v[36:37], v[186:187], v[196:197] op_sel_hi:[0,1]
	v_pk_mul_f32 v[34:35], v[50:51], v[34:35] op_sel:[0,1] op_sel_hi:[1,0]
	v_pk_mul_f32 v[36:37], v[52:53], v[36:37] op_sel:[0,1] op_sel_hi:[1,0]

; __device__ __forceinline__ v4u packf8(const float (&f)[8]) { v4u w; w.x = pk2(f[0], f[1]); w.y = pk2(f[2], f[3]); w.z = pk2(f[4], f[5]); w.w = pk2(f[6], f[7]); return w; }
; __device__ __forceinline__ void bprep_item(const Params& P, LAS unsigned char* lds, int item, int tid, int lane, int wave) {
;     ...
;             *(v4u*)(kdst + (kvblk * 8 + h) * 4096 + piece) = xchg8x8(xs, lane, packf8(f));
;             {
;                 float* ko = nullptr;
;                 if (mode == 0) { const int ts = c * 64 + tl; if (ts >= TP - 512) ko = P.out + O_KP + (((size_t)s * 512 + (ts - (TP - 512))) * 8 + h) * 64 + 8 * part; }
;                 else if (mode == 1 && valid) ko = P.out + O_KS + (((size_t)s * 16 + tl) * 8 + h) * 64 + 8 * part;
;                 if (ko) { ((f32x4*)ko)[0] = (f32x4){f[0], f[1], f[2], f[3]}; ((f32x4*)ko)[1] = (f32x4){f[4], f[5], f[6], f[7]}; }
.LBB0_536:
	v_cvt_pk_bf16_f32 v186, v38, v39
	v_cvt_pk_bf16_f32 v187, v40, v41
	v_cvt_pk_bf16_f32 v188, v34, v35
	v_cvt_pk_bf16_f32 v189, v36, v37
	ds_write_b128 v190, v[186:189]
	ds_read_b128 v[186:189], v191
	s_mov_b32 s53, s9
	s_lshl_b64 s[18:19], s[52:53], 12
	v_lshl_add_u64 v[194:195], v[178:179], 0, s[18:19]
	s_waitcnt lgkmcnt(0)
	global_store_dwordx4 v[194:195], v[186:189], off
	s_nop 1
	v_or_b32_e32 v186, s52, v150
	v_mov_b32_e32 v187, v1
	v_lshlrev_b64 v[186:187], 8, v[186:187]
	v_lshl_add_u64 v[188:189], v[182:183], 0, v[186:187]
	v_cmp_ne_u64_e32 vcc, 0, v[188:189]
	s_and_b64 s[18:19], s[6:7], vcc
	s_and_saveexec_b64 s[56:57], s[18:19]
	s_cbranch_execz .LBB0_538
	global_store_dwordx4 v[188:189], v[38:41], off nt
	global_store_dwordx4 v[188:189], v[34:37], off offset:16 nt

; __device__ __forceinline__ void bprep_item(const Params& P, LAS unsigned char* lds, int item, int tid, int lane, int wave) {
;     ...
;         for (int hi = 0; hi < 4; ++hi) { const int h = hb4 + hi;
;             float f[8];
;             if (mode != 2) {
;                 unpack8(wq_[hi], f); float ss = 0.f;
; #pragma unroll
;                 for (int i = 0; i < 8; ++i) ss += f[i] * f[i];
;                 ss += __shfl_xor(ss, 1); ss += __shfl_xor(ss, 2); ss += __shfl_xor(ss, 4);
;                 float rstd = __builtin_amdgcn_rsqf(ss * (1.0f / 64.0f) + 1e-6f);
; #pragma unroll
;                 for (int i = 0; i < 8; ++i) f[i] = f[i] * (rstd * 0.18033688011f) * qg[i];
;                 *(v4u*)(qdst + (qblk * 8 + h) * 4096 + piece) = xchg8x8(xs, lane, packf8(f));
;                 unpack8(wk_[hi], f); ss = 0.f;
; #pragma unroll
;                 for (int i = 0; i < 8; ++i) ss += f[i] * f[i];
;                 ss += __shfl_xor(ss, 1); ss += __shfl_xor(ss, 2); ss += __shfl_xor(ss, 4);
;                 rstd = __builtin_amdgcn_rsqf(ss * (1.0f / 64.0f) + 1e-6f);
; #pragma unroll
;                 for (int i = 0; i < 8; ++i) f[i] = f[i] * rstd * kg[i];
;             } else { f[0] = ck_[hi][0][0]; f[1] = ck_[hi][0][1]; f[2] = ck_[hi][0][2]; f[3] = ck_[hi][0][3]; f[4] = ck_[hi][1][0]; f[5] = ck_[hi][1][1]; f[6] = ck_[hi][1][2]; f[7] = ck_[hi][1][3]; }
;             *(v4u*)(kdst + (kvblk * 8 + h) * 4096 + piece) = xchg8x8(xs, lane, packf8(f));
;             {
;                 float* ko = nullptr;
;                 if (mode == 0) { const int ts = c * 64 + tl; if (ts >= TP - 512) ko = P.out + O_KP + (((size_t)s * 512 + (ts - (TP - 512))) * 8 + h) * 64 + 8 * part; }
;                 else if (mode == 1 && valid) ko = P.out + O_KS + (((size_t)s * 16 + tl) * 8 + h) * 64 + 8 * part;
;                 if (ko) { ((f32x4*)ko)[0] = (f32x4){f[0], f[1], f[2], f[3]}; ((f32x4*)ko)[1] = (f32x4){f[4], f[5], f[6], f[7]}; }
;             }
;             if (mode != 2) unpack8(wv_[hi], f);
;             else { f[0] = cv_[hi][0][0]; f[1] = cv_[hi][0][1]; f[2] = cv_[hi][0][2]; f[3] = cv_[hi][0][3]; f[4] = cv_[hi][1][0]; f[5] = cv_[hi][1][1]; f[6] = cv_[hi][1][2]; f[7] = cv_[hi][1][3]; }
;             {
;                 float* vo = nullptr;
.LBB0_543:
	s_or_b64 exec, exec, s[56:57]
	v_cvt_pk_bf16_f32 v34, v34, v35
	v_cvt_pk_bf16_f32 v35, v36, v37
	v_cvt_pk_bf16_f32 v36, v38, v39
	v_lshl_add_u32 v38, s52, 6, v138
	v_cvt_pk_bf16_f32 v37, v40, v41
	v_mad_u64_u32 v[38:39], s[18:19], v38, s58, v[158:159]
	s_and_b64 vcc, exec, s[4:5]
	s_mov_b64 s[52:53], -1
	ds_write_b128 v38, v[34:37]
	s_cbranch_vccnz .LBB0_545
	v_lshlrev_b32_e32 v194, 16, v122
	v_and_b32_e32 v195, 0xffff0000, v122
	v_and_b32_e32 v35, 64, v192
	v_lshlrev_b32_e32 v186, 16, v123
	v_and_b32_e32 v187, 0xffff0000, v123
	v_pk_mul_f32 v[196:197], v[194:195], v[194:195]
	v_xor_b32_e32 v34, 1, v192
	v_add_u32_e32 v193, 64, v35
	v_pk_mul_f32 v[188:189], v[186:187], v[186:187]
	v_add_f32_e32 v196, v196, v197
	v_cmp_lt_i32_e32 vcc, v34, v193
	v_lshlrev_b32_e32 v38, 16, v124
	v_and_b32_e32 v39, 0xffff0000, v124
	v_add_f32_e32 v188, v188, v196
	v_cndmask_b32_e32 v34, v192, v34, vcc
	v_pk_mul_f32 v[40:41], v[38:39], v[38:39]
	v_add_f32_e32 v188, v189, v188
	v_lshlrev_b32_e32 v208, 2, v34
	v_lshlrev_b32_e32 v34, 16, v125
	v_and_b32_e32 v35, 0xffff0000, v125
	v_add_f32_e32 v40, v40, v188
	v_pk_mul_f32 v[36:37], v[34:35], v[34:35]
	v_add_f32_e32 v40, v41, v40
	v_add_f32_e32 v36, v36, v40
	v_add_f32_e32 v36, v37, v36
	ds_bpermute_b32 v37, v208, v36
	v_xor_b32_e32 v40, 2, v192
	v_cmp_lt_i32_e32 vcc, v40, v193
	v_lshlrev_b32_e32 v200, 16, v118
	v_and_b32_e32 v201, 0xffff0000, v118
	v_cndmask_b32_e32 v40, v192, v40, vcc
	v_lshlrev_b32_e32 v209, 2, v40
	s_waitcnt lgkmcnt(0)
	v_add_f32_e32 v36, v36, v37
	ds_bpermute_b32 v37, v209, v36
	v_xor_b32_e32 v40, 4, v192
	v_cmp_lt_i32_e32 vcc, v40, v193
	v_pk_mul_f32 v[202:203], v[200:201], v[200:201]
	v_lshlrev_b32_e32 v204, 16, v119
	v_cndmask_b32_e32 v40, v192, v40, vcc
	v_lshlrev_b32_e32 v193, 2, v40
	s_waitcnt lgkmcnt(0)
	v_add_f32_e32 v36, v36, v37
	ds_bpermute_b32 v37, v193, v36
	v_and_b32_e32 v205, 0xffff0000, v119
	v_pk_mul_f32 v[206:207], v[204:205], v[204:205]
	v_and_b32_e32 v188, 0xffff0000, v120
	v_lshlrev_b32_e32 v189, 16, v120
	s_waitcnt lgkmcnt(0)
	v_add_f32_e32 v36, v36, v37
	v_fmamk_f32 v36, v36, 0x3c800000, v171
	v_rsq_f32_e32 v36, v36
	v_and_b32_e32 v196, 0xffff0000, v121
	v_lshlrev_b32_e32 v197, 16, v121
	v_pk_mul_f32 v[198:199], v[196:197], v[196:197]
	v_mul_f32_e32 v36, 0x3e38aa3b, v36
	v_pk_mul_f32 v[40:41], v[36:37], v[194:195] op_sel_hi:[0,1]
	v_add_f32_e32 v37, v202, v203
	v_add_f32_e32 v37, v206, v37
	v_pk_mul_f32 v[194:195], v[188:189], v[188:189]
	v_add_f32_e32 v37, v207, v37
	v_add_f32_e32 v37, v195, v37
	v_add_f32_e32 v37, v194, v37
	v_add_f32_e32 v37, v199, v37
	v_add_f32_e32 v37, v198, v37
	ds_bpermute_b32 v194, v208, v37
	v_pk_mul_f32 v[186:187], v[36:37], v[186:187] op_sel_hi:[0,1]
	v_pk_mul_f32 v[38:39], v[36:37], v[38:39] op_sel_hi:[0,1]
	v_pk_mul_f32 v[40:41], v[46:47], v[40:41]
	v_pk_mul_f32 v[186:187], v[48:49], v[186:187]
	s_waitcnt lgkmcnt(0)
	v_add_f32_e32 v37, v37, v194
	ds_bpermute_b32 v198, v209, v37
	v_pk_mul_f32 v[34:35], v[36:37], v[34:35] op_sel_hi:[0,1]
	v_pk_mul_f32 v[194:195], v[44:45], v[34:35]
	v_cvt_pk_bf16_f32 v34, v40, v41
	v_pk_mul_f32 v[38:39], v[42:43], v[38:39]
	s_waitcnt lgkmcnt(0)
	v_add_f32_e32 v40, v37, v198
	ds_bpermute_b32 v41, v193, v40
	v_cvt_pk_bf16_f32 v35, v186, v187
	v_cvt_pk_bf16_f32 v36, v38, v39
	v_cvt_pk_bf16_f32 v37, v194, v195
	ds_write_b128 v190, v[34:37]
	s_waitcnt lgkmcnt(1)
	v_add_f32_e32 v38, v40, v41
	ds_read_b128 v[34:37], v191
	v_fmamk_f32 v38, v38, 0x3c800000, v171
	v_rsq_f32_e32 v186, v38
	s_lshl_b32 s8, s48, 12
	v_lshl_add_u64 v[38:39], v[180:181], 0, s[8:9]
	s_waitcnt lgkmcnt(0)
	global_store_dwordx4 v[38:39], v[34:37], off nt
	s_mov_b64 s[52:53], 0
	s_nop 0
	v_pk_mul_f32 v[34:35], v[186:187], v[200:201] op_sel_hi:[0,1]
	v_pk_mul_f32 v[38:39], v[54:55], v[34:35]
	v_pk_mul_f32 v[34:35], v[186:187], v[204:205] op_sel_hi:[0,1]
	v_pk_mul_f32 v[40:41], v[56:57], v[34:35]
	v_pk_mul_f32 v[34:35], v[186:187], v[188:189] op_sel_hi:[0,1]
	v_pk_mul_f32 v[36:37], v[186:187], v[196:197] op_sel_hi:[0,1]
	v_pk_mul_f32 v[34:35], v[50:51], v[34:35] op_sel:[0,1] op_sel_hi:[1,0]
	v_pk_mul_f32 v[36:37], v[52:53], v[36:37] op_sel:[0,1] op_sel_hi:[1,0]

; __device__ __forceinline__ v4u packf8(const float (&f)[8]) { v4u w; w.x = pk2(f[0], f[1]); w.y = pk2(f[2], f[3]); w.z = pk2(f[4], f[5]); w.w = pk2(f[6], f[7]); return w; }
; __device__ __forceinline__ void bprep_item(const Params& P, LAS unsigned char* lds, int item, int tid, int lane, int wave) {
;     ...
;             *(v4u*)(kdst + (kvblk * 8 + h) * 4096 + piece) = xchg8x8(xs, lane, packf8(f));
;             {
;                 float* ko = nullptr;
;                 if (mode == 0) { const int ts = c * 64 + tl; if (ts >= TP - 512) ko = P.out + O_KP + (((size_t)s * 512 + (ts - (TP - 512))) * 8 + h) * 64 + 8 * part; }
;                 else if (mode == 1 && valid) ko = P.out + O_KS + (((size_t)s * 16 + tl) * 8 + h) * 64 + 8 * part;
;                 if (ko) { ((f32x4*)ko)[0] = (f32x4){f[0], f[1], f[2], f[3]}; ((f32x4*)ko)[1] = (f32x4){f[4], f[5], f[6], f[7]}; }
.LBB0_547:
	v_cvt_pk_bf16_f32 v186, v38, v39
	v_cvt_pk_bf16_f32 v187, v40, v41
	v_cvt_pk_bf16_f32 v188, v34, v35
	v_cvt_pk_bf16_f32 v189, v36, v37
	ds_write_b128 v190, v[186:189]
	ds_read_b128 v[186:189], v191
	s_mov_b32 s49, s9
	s_lshl_b64 s[18:19], s[48:49], 12
	v_lshl_add_u64 v[194:195], v[178:179], 0, s[18:19]
	s_waitcnt lgkmcnt(0)
	global_store_dwordx4 v[194:195], v[186:189], off
	s_nop 1
	v_or_b32_e32 v186, s48, v150
	v_mov_b32_e32 v187, v1
	v_lshlrev_b64 v[186:187], 8, v[186:187]
	v_lshl_add_u64 v[188:189], v[182:183], 0, v[186:187]
	v_cmp_ne_u64_e32 vcc, 0, v[188:189]
	s_and_b64 s[18:19], s[6:7], vcc
	s_and_saveexec_b64 s[52:53], s[18:19]
	s_cbranch_execz .LBB0_549
	global_store_dwordx4 v[188:189], v[38:41], off nt
	global_store_dwordx4 v[188:189], v[34:37], off offset:16 nt

; __device__ __forceinline__ void bprep_item(const Params& P, LAS unsigned char* lds, int item, int tid, int lane, int wave) {
;     ...
;         for (int hi = 0; hi < 4; ++hi) { const int h = hb4 + hi;
;             float f[8];
;             if (mode != 2) {
;                 unpack8(wq_[hi], f); float ss = 0.f;
; #pragma unroll
;                 for (int i = 0; i < 8; ++i) ss += f[i] * f[i];
;                 ss += __shfl_xor(ss, 1); ss += __shfl_xor(ss, 2); ss += __shfl_xor(ss, 4);
;                 float rstd = __builtin_amdgcn_rsqf(ss * (1.0f / 64.0f) + 1e-6f);
; #pragma unroll
;                 for (int i = 0; i < 8; ++i) f[i] = f[i] * (rstd * 0.18033688011f) * qg[i];
;                 *(v4u*)(qdst + (qblk * 8 + h) * 4096 + piece) = xchg8x8(xs, lane, packf8(f));
;                 unpack8(wk_[hi], f); ss = 0.f;
; #pragma unroll
;                 for (int i = 0; i < 8; ++i) ss += f[i] * f[i];
;                 ss += __shfl_xor(ss, 1); ss += __shfl_xor(ss, 2); ss += __shfl_xor(ss, 4);
;                 rstd = __builtin_amdgcn_rsqf(ss * (1.0f / 64.0f) + 1e-6f);
; #pragma unroll
;                 for (int i = 0; i < 8; ++i) f[i] = f[i] * rstd * kg[i];
;             } else { f[0] = ck_[hi][0][0]; f[1] = ck_[hi][0][1]; f[2] = ck_[hi][0][2]; f[3] = ck_[hi][0][3]; f[4] = ck_[hi][1][0]; f[5] = ck_[hi][1][1]; f[6] = ck_[hi][1][2]; f[7] = ck_[hi][1][3]; }
;             *(v4u*)(kdst + (kvblk * 8 + h) * 4096 + piece) = xchg8x8(xs, lane, packf8(f));
;             {
;                 float* ko = nullptr;
;                 if (mode == 0) { const int ts = c * 64 + tl; if (ts >= TP - 512) ko = P.out + O_KP + (((size_t)s * 512 + (ts - (TP - 512))) * 8 + h) * 64 + 8 * part; }
;                 else if (mode == 1 && valid) ko = P.out + O_KS + (((size_t)s * 16 + tl) * 8 + h) * 64 + 8 * part;
;                 if (ko) { ((f32x4*)ko)[0] = (f32x4){f[0], f[1], f[2], f[3]}; ((f32x4*)ko)[1] = (f32x4){f[4], f[5], f[6], f[7]}; }
;             }
;             if (mode != 2) unpack8(wv_[hi], f);
;             else { f[0] = cv_[hi][0][0]; f[1] = cv_[hi][0][1]; f[2] = cv_[hi][0][2]; f[3] = cv_[hi][0][3]; f[4] = cv_[hi][1][0]; f[5] = cv_[hi][1][1]; f[6] = cv_[hi][1][2]; f[7] = cv_[hi][1][3]; }
;             {
;                 float* vo = nullptr;
.LBB0_552:
	s_andn2_b64 vcc, exec, s[52:53]
	v_lshl_add_u64 v[186:187], v[184:185], 0, v[186:187]
	v_cmp_ne_u64_e32 vcc, 0, v[186:187]
	s_and_b64 s[18:19], s[6:7], vcc
	s_and_saveexec_b64 s[52:53], s[18:19]
	s_cbranch_execz .LBB0_554
	global_store_dwordx4 v[186:187], v[34:37], off nt
	global_store_dwordx4 v[186:187], v[38:41], off offset:16 nt
.LBB0_554:
	s_or_b64 exec, exec, s[52:53]
	v_cvt_pk_bf16_f32 v34, v34, v35
	v_cvt_pk_bf16_f32 v35, v36, v37
	v_cvt_pk_bf16_f32 v36, v38, v39
	v_lshl_add_u32 v38, s48, 6, v138
	v_cvt_pk_bf16_f32 v37, v40, v41
	v_mad_u64_u32 v[38:39], s[18:19], v38, s58, v[158:159]
	s_and_b64 vcc, exec, s[4:5]
	s_mov_b64 s[48:49], -1
	ds_write_b128 v38, v[34:37]
	s_cbranch_vccnz .LBB0_556
	v_lshlrev_b32_e32 v194, 16, v134
	v_and_b32_e32 v195, 0xffff0000, v134
	v_and_b32_e32 v35, 64, v192
	v_lshlrev_b32_e32 v186, 16, v135
	v_and_b32_e32 v187, 0xffff0000, v135
	v_pk_mul_f32 v[196:197], v[194:195], v[194:195]
	v_xor_b32_e32 v34, 1, v192
	v_add_u32_e32 v193, 64, v35
	v_pk_mul_f32 v[188:189], v[186:187], v[186:187]
	v_add_f32_e32 v196, v196, v197
	v_cmp_lt_i32_e32 vcc, v34, v193
	v_lshlrev_b32_e32 v38, 16, v136
	v_and_b32_e32 v39, 0xffff0000, v136
	v_add_f32_e32 v188, v188, v196
	v_cndmask_b32_e32 v34, v192, v34, vcc
	v_pk_mul_f32 v[40:41], v[38:39], v[38:39]
	v_add_f32_e32 v188, v189, v188
	v_lshlrev_b32_e32 v208, 2, v34
	v_lshlrev_b32_e32 v34, 16, v137
	v_and_b32_e32 v35, 0xffff0000, v137
	v_add_f32_e32 v40, v40, v188
	v_pk_mul_f32 v[36:37], v[34:35], v[34:35]
	v_add_f32_e32 v40, v41, v40
	v_add_f32_e32 v36, v36, v40
	v_add_f32_e32 v36, v37, v36
	ds_bpermute_b32 v37, v208, v36
	v_xor_b32_e32 v40, 2, v192
	v_cmp_lt_i32_e32 vcc, v40, v193
	v_lshlrev_b32_e32 v200, 16, v130
	v_and_b32_e32 v201, 0xffff0000, v130
	v_cndmask_b32_e32 v40, v192, v40, vcc
	v_lshlrev_b32_e32 v209, 2, v40
	s_waitcnt lgkmcnt(0)
	v_add_f32_e32 v36, v36, v37
	ds_bpermute_b32 v37, v209, v36
	v_xor_b32_e32 v40, 4, v192
	v_cmp_lt_i32_e32 vcc, v40, v193
	v_pk_mul_f32 v[202:203], v[200:201], v[200:201]
	v_lshlrev_b32_e32 v204, 16, v131
	v_cndmask_b32_e32 v40, v192, v40, vcc
	v_lshlrev_b32_e32 v193, 2, v40
	s_waitcnt lgkmcnt(0)
	v_add_f32_e32 v36, v36, v37
	ds_bpermute_b32 v37, v193, v36
	v_and_b32_e32 v205, 0xffff0000, v131
	v_pk_mul_f32 v[206:207], v[204:205], v[204:205]
	v_and_b32_e32 v188, 0xffff0000, v132
	v_lshlrev_b32_e32 v189, 16, v132
	s_waitcnt lgkmcnt(0)
	v_add_f32_e32 v36, v36, v37
	v_fmamk_f32 v36, v36, 0x3c800000, v171
	v_rsq_f32_e32 v36, v36
	v_and_b32_e32 v196, 0xffff0000, v133
	v_lshlrev_b32_e32 v197, 16, v133
	v_pk_mul_f32 v[198:199], v[196:197], v[196:197]
	v_mul_f32_e32 v36, 0x3e38aa3b, v36
	v_pk_mul_f32 v[40:41], v[36:37], v[194:195] op_sel_hi:[0,1]
	v_add_f32_e32 v37, v202, v203
	v_add_f32_e32 v37, v206, v37
	v_pk_mul_f32 v[194:195], v[188:189], v[188:189]
	v_add_f32_e32 v37, v207, v37
	v_add_f32_e32 v37, v195, v37
	v_add_f32_e32 v37, v194, v37
	v_add_f32_e32 v37, v199, v37
	v_add_f32_e32 v37, v198, v37
	ds_bpermute_b32 v194, v208, v37
	v_pk_mul_f32 v[186:187], v[36:37], v[186:187] op_sel_hi:[0,1]
	v_pk_mul_f32 v[38:39], v[36:37], v[38:39] op_sel_hi:[0,1]
	v_pk_mul_f32 v[40:41], v[46:47], v[40:41]
	v_pk_mul_f32 v[186:187], v[48:49], v[186:187]
	s_waitcnt lgkmcnt(0)
	v_add_f32_e32 v37, v37, v194
	ds_bpermute_b32 v198, v209, v37
	v_pk_mul_f32 v[34:35], v[36:37], v[34:35] op_sel_hi:[0,1]
	v_pk_mul_f32 v[194:195], v[44:45], v[34:35]
	v_cvt_pk_bf16_f32 v34, v40, v41
	v_pk_mul_f32 v[38:39], v[42:43], v[38:39]
	s_waitcnt lgkmcnt(0)
	v_add_f32_e32 v40, v37, v198
	ds_bpermute_b32 v41, v193, v40
	v_cvt_pk_bf16_f32 v35, v186, v187
	v_cvt_pk_bf16_f32 v36, v38, v39
	v_cvt_pk_bf16_f32 v37, v194, v195
	ds_write_b128 v190, v[34:37]
	s_waitcnt lgkmcnt(1)
	v_add_f32_e32 v38, v40, v41
	ds_read_b128 v[34:37], v191
	v_fmamk_f32 v38, v38, 0x3c800000, v171
	v_rsq_f32_e32 v186, v38
	s_lshl_b32 s8, s46, 12
	v_lshl_add_u64 v[38:39], v[180:181], 0, s[8:9]
	s_waitcnt lgkmcnt(0)
	global_store_dwordx4 v[38:39], v[34:37], off nt
	s_mov_b64 s[48:49], 0
	s_nop 0
	v_pk_mul_f32 v[34:35], v[186:187], v[200:201] op_sel_hi:[0,1]
	v_pk_mul_f32 v[38:39], v[54:55], v[34:35]
	v_pk_mul_f32 v[34:35], v[186:187], v[204:205] op_sel_hi:[0,1]
	v_pk_mul_f32 v[40:41], v[56:57], v[34:35]
	v_pk_mul_f32 v[34:35], v[186:187], v[188:189] op_sel_hi:[0,1]
	v_pk_mul_f32 v[36:37], v[186:187], v[196:197] op_sel_hi:[0,1]
	v_pk_mul_f32 v[34:35], v[50:51], v[34:35] op_sel:[0,1] op_sel_hi:[1,0]
	v_pk_mul_f32 v[36:37], v[52:53], v[36:37] op_sel:[0,1] op_sel_hi:[1,0]

; __device__ __forceinline__ v4u packf8(const float (&f)[8]) { v4u w; w.x = pk2(f[0], f[1]); w.y = pk2(f[2], f[3]); w.z = pk2(f[4], f[5]); w.w = pk2(f[6], f[7]); return w; }
; __device__ __forceinline__ void bprep_item(const Params& P, LAS unsigned char* lds, int item, int tid, int lane, int wave) {
;     ...
;             *(v4u*)(kdst + (kvblk * 8 + h) * 4096 + piece) = xchg8x8(xs, lane, packf8(f));
;             {
;                 float* ko = nullptr;
;                 if (mode == 0) { const int ts = c * 64 + tl; if (ts >= TP - 512) ko = P.out + O_KP + (((size_t)s * 512 + (ts - (TP - 512))) * 8 + h) * 64 + 8 * part; }
;                 else if (mode == 1 && valid) ko = P.out + O_KS + (((size_t)s * 16 + tl) * 8 + h) * 64 + 8 * part;
;                 if (ko) { ((f32x4*)ko)[0] = (f32x4){f[0], f[1], f[2], f[3]}; ((f32x4*)ko)[1] = (f32x4){f[4], f[5], f[6], f[7]}; }
.LBB0_558:
	v_cvt_pk_bf16_f32 v186, v38, v39
	v_cvt_pk_bf16_f32 v187, v40, v41
	v_cvt_pk_bf16_f32 v188, v34, v35
	v_cvt_pk_bf16_f32 v189, v36, v37
	ds_write_b128 v190, v[186:189]
	ds_read_b128 v[186:189], v191
	s_mov_b32 s47, s9
	s_lshl_b64 s[18:19], s[46:47], 12
	v_lshl_add_u64 v[194:195], v[178:179], 0, s[18:19]
	s_waitcnt lgkmcnt(0)
	global_store_dwordx4 v[194:195], v[186:189], off
	s_nop 1
	v_or_b32_e32 v186, s46, v150
	v_mov_b32_e32 v187, v1
	v_lshlrev_b64 v[186:187], 8, v[186:187]
	v_lshl_add_u64 v[188:189], v[182:183], 0, v[186:187]
	v_cmp_ne_u64_e32 vcc, 0, v[188:189]
	s_and_b64 s[18:19], s[6:7], vcc
	s_and_saveexec_b64 s[48:49], s[18:19]
	s_cbranch_execz .LBB0_560
	global_store_dwordx4 v[188:189], v[38:41], off nt
	global_store_dwordx4 v[188:189], v[34:37], off offset:16 nt

; __device__ __forceinline__ void bprep_item(const Params& P, LAS unsigned char* lds, int item, int tid, int lane, int wave) {
;     ...
;                 float* vo = nullptr;
;                 if (mode == 0) { const int ts = c * 64 + tl; if (ts >= TP - 512) vo = P.out + O_VP + (((size_t)s * 512 + (ts - (TP - 512))) * 8 + h) * 64 + 8 * part; }
;                 else if (mode == 1 && valid) vo = P.out + O_VS + (((size_t)s * 16 + tl) * 8 + h) * 64 + 8 * part;
;                 if (vo) { ((f32x4*)vo)[0] = (f32x4){f[0], f[1], f[2], f[3]}; ((f32x4*)vo)[1] = (f32x4){f[4], f[5], f[6], f[7]}; }
.LBB0_563:
	s_andn2_b64 vcc, exec, s[4:5]
	v_lshl_add_u64 v[186:187], v[184:185], 0, v[186:187]
	v_cmp_ne_u64_e32 vcc, 0, v[186:187]
	s_and_b64 s[18:19], s[6:7], vcc
	s_and_saveexec_b64 s[4:5], s[18:19]
	s_cbranch_execz .LBB0_496
	global_store_dwordx4 v[186:187], v[34:37], off nt
	global_store_dwordx4 v[186:187], v[38:41], off offset:16 nt
	s_branch .LBB0_496
